# attention units: Q fragments (read once per unit) loaded with nt
# baseline (speedup 1.0000x reference)
; template <int DQK, int SDEPTH, int QL, bool NOMAX, int ldq, int ldk, int ldv, int ldo> ...
;     ...
;     float m_reg = -1e30f, l_reg = 0; f32x16 o[4] = {}; bf16x8 qr[NQR];
;     const bf16_t* Qw = Qb + (size_t)(wid * QBLK + r32) * ldq + hi * 8;
; #pragma unroll
;     for (int d0 = 0; d0 < NQR; ++d0) qr[d0] = *reinterpret_cast<const bf16x8*>(Qw + d0 * 16);
.LBB0_1465:
	v_mbcnt_lo_u32_b32 v190, -1, 0
	v_mbcnt_hi_u32_b32 v190, -1, v190
	s_andn2_b64 vcc, exec, s[18:19]
	v_and_b32_e32 v192, 31, v190
	v_or_b32_e32 v0, s10, v192
	v_ashrrev_i32_e32 v1, 31, v0
	v_bfe_u32 v191, v190, 5, 1
	v_lshlrev_b64 v[0:1], 12, v[0:1]
	v_lshl_add_u64 v[0:1], s[28:29], 0, v[0:1]
	v_lshlrev_b32_e32 v32, 4, v191
	v_lshl_add_u64 v[0:1], v[0:1], 0, v[32:33]
	global_load_dwordx4 v[142:145], v[0:1], off nt
	global_load_dwordx4 v[138:141], v[0:1], off offset:32 nt
	global_load_dwordx4 v[134:137], v[0:1], off offset:64 nt
	global_load_dwordx4 v[130:133], v[0:1], off offset:96 nt
	global_load_dwordx4 v[126:129], v[0:1], off offset:128 nt
	global_load_dwordx4 v[122:125], v[0:1], off offset:160 nt
	global_load_dwordx4 v[118:121], v[0:1], off offset:192 nt
	global_load_dwordx4 v[114:117], v[0:1], off offset:224 nt
	s_cbranch_vccnz .LBB0_1467
	s_setprio 1

; template <int DQK, int SDEPTH, int QL, bool NOMAX, int ldq, int ldk, int ldv, int ldo> ...
;     ...
;     float m_reg = -1e30f, l_reg = 0; f32x16 o[4] = {}; bf16x8 qr[NQR];
;     const bf16_t* Qw = Qb + (size_t)(wid * QBLK + r32) * ldq + hi * 8;
; #pragma unroll
;     for (int d0 = 0; d0 < NQR; ++d0) qr[d0] = *reinterpret_cast<const bf16x8*>(Qw + d0 * 16);
.LBB0_2008:
	s_and_b64 vcc, exec, s[4:5]
	s_cbranch_vccz .LBB0_1860
	v_mbcnt_lo_u32_b32 v232, -1, 0
	v_mbcnt_hi_u32_b32 v232, -1, v232
	v_mov_b64_e32 v[0:1], s[28:29]
	v_and_b32_e32 v240, 31, v232
	v_bfe_u32 v233, v232, 5, 1
	v_or_b32_e32 v2, s10, v240
	s_movk_i32 s4, 0xc00
	v_mad_i64_i32 v[0:1], s[4:5], v2, s4, v[0:1]
	v_lshlrev_b32_e32 v32, 4, v233
	v_lshl_add_u64 v[0:1], v[0:1], 0, v[32:33]
	global_load_dwordx4 v[158:161], v[0:1], off nt
	global_load_dwordx4 v[154:157], v[0:1], off offset:32 nt
	global_load_dwordx4 v[150:153], v[0:1], off offset:64 nt
	global_load_dwordx4 v[146:149], v[0:1], off offset:96 nt
	global_load_dwordx4 v[142:145], v[0:1], off offset:128 nt
	global_load_dwordx4 v[138:141], v[0:1], off offset:160 nt
	global_load_dwordx4 v[134:137], v[0:1], off offset:192 nt
	global_load_dwordx4 v[130:133], v[0:1], off offset:224 nt
	global_load_dwordx4 v[126:129], v[0:1], off offset:256 nt
	global_load_dwordx4 v[122:125], v[0:1], off offset:288 nt
	global_load_dwordx4 v[118:121], v[0:1], off offset:320 nt
	global_load_dwordx4 v[114:117], v[0:1], off offset:352 nt
	s_andn2_b64 vcc, exec, s[18:19]
	s_cbranch_vccnz .LBB0_2011
	s_setprio 1

; template <int DQK, int SDEPTH, int QL, bool NOMAX, int ldq, int ldk, int ldv, int ldo> ...
;     ...
;     float m_reg = -1e30f, l_reg = 0; f32x16 o[4] = {}; bf16x8 qr[NQR];
;     const bf16_t* Qw = Qb + (size_t)(wid * QBLK + r32) * ldq + hi * 8;
; #pragma unroll
;     for (int d0 = 0; d0 < NQR; ++d0) qr[d0] = *reinterpret_cast<const bf16x8*>(Qw + d0 * 16);
.LBB0_2295:
	v_mbcnt_lo_u32_b32 v162, -1, 0
	v_mbcnt_hi_u32_b32 v162, -1, v162
	s_andn2_b64 vcc, exec, s[16:17]
	v_and_b32_e32 v164, 31, v162
	v_or_b32_e32 v0, s8, v164
	v_ashrrev_i32_e32 v1, 31, v0
	v_bfe_u32 v163, v162, 5, 1
	v_lshlrev_b64 v[0:1], 11, v[0:1]
	v_lshl_add_u64 v[0:1], s[28:29], 0, v[0:1]
	v_lshlrev_b32_e32 v32, 4, v163
	v_lshl_add_u64 v[0:1], v[0:1], 0, v[32:33]
	global_load_dwordx4 v[126:129], v[0:1], off nt
	global_load_dwordx4 v[122:125], v[0:1], off offset:32 nt
	global_load_dwordx4 v[118:121], v[0:1], off offset:64 nt
	global_load_dwordx4 v[114:117], v[0:1], off offset:96 nt
	s_cbranch_vccnz .LBB0_2297
	s_setprio 1
